# P3 scan: hand-scheduled compute waves, loader reorder+rewrite (DPP prefix, d16_hi writes), quad-split triangular solve, role swap 6/7
# speedup vs baseline: 1.0597x; 1.0597x over previous
; template <bool RWKV> __device__ __forceinline__ void scan_prep_m1(const LAS unsigned char* buf, LAS unsigned char* img, int lane) {
;     const int r = lane & 31, h = lane >> 5;
;     f32x16 gh;
; #pragma unroll
;     for (int i = 0; i < 16; ++i) gh[i] = 0.f;
; #pragma unroll
;     for (int kb = 0; kb < 4; ++kb) { const bf16x8 a = *(const LAS bf16x8*)(buf + SB_XB + r * 144 + (16 * kb + 8 * h) * 2), b = *(const LAS bf16x8*)(buf + SB_XA + r * 144 + (16 * kb + 8 * h) * 2); gh = MFMA32(a, b, gh); }
;     const int lim = r < 16 ? r : r - 15;
; #pragma unroll
;     for (int g = 0; g < 2; ++g) { const int t0 = 8 * g + 4 * h; float x[4], y[4];
; #pragma unroll
;         for (int q = 0; q < 4; ++q) { x[q] = (t0 + q < lim) ? gh[4 * g + q] : 0.f; y[q] = (t0 + q < lim) ? gh[8 + 4 * g + q] : 0.f; }
;         if (RWKV && r < 16) {
; #pragma unroll
;             for (int q = 0; q < 4; ++q) *(LAS float*)(img + SW_GR + ((t0 + q) * 16 + r) * 4) = x[q]; }
;         u32x2 wv; wv.x = r >= 16 ? cvt2(x[0], x[1]) : 0u; wv.y = r >= 16 ? cvt2(x[2], x[3]) : 0u; *(LAS u32x2*)(img + SW_GYT + r * 48 + t0 * 2) = wv;
;         wv.x = cvt2(y[0], y[1]); wv.y = cvt2(y[2], y[3]); *(LAS u32x2*)(img + SW_HT + r * 48 + t0 * 2) = wv; }
; }
; template <bool RWKV> __device__ __forceinline__ void scan_item(LAS unsigned char* lds, const ScanSrc& S, int wid, int lane) {
;     f32x16 T[2];
; #pragma unroll
;     for (int a = 0; a < 2; ++a)
; #pragma unroll
;         for (int i = 0; i < 16; ++i) T[a][i] = 0.f;
;     const bool is_ld = (wid == 4) | (wid == 5) | (wid == 3) | (wid == 7); const bool is_prep = wid == 2;
;     const int lt = (wid == 4 ? 0 : wid == 5 ? 64 : wid == 3 ? 128 : 192) + lane;
;     ScanLd L;
;     constexpr int NCH = T_SEQ / SC_CH;
;     ...
;     const bool is_inv = wid == 6;
;     if (is_ld) { scan_load_issue<RWKV>(L, S, 0, lt); scan_load_finish<RWKV>(lds, L, lt); scan_load_issue<RWKV>(L, S, 1, lt); scan_load_finish<RWKV>(lds + SC_BUF, L, lt);
;                  scan_load_issue<RWKV>(L, S, 2, lt); scan_load_finish<RWKV>(lds + 2 * SC_BUF, L, lt); scan_load_issue<RWKV>(L, S, 3, lt); }
;     __syncthreads();
;     if (is_prep) { scan_prep_m1<RWKV>(lds, lds + SC_IMG, lane); scan_prep_m1<RWKV>(lds + SC_BUF, lds + SC_IMG + SW_SIZE, lane); }
;     SC_BAR();
;     if (is_inv) scan_prep_inv<RWKV>(lds + SC_IMG, lane);
;     SC_BAR();
;     int b0 = 0, i0 = 0;
.LBB0_527:
	s_or_b64 exec, exec, s[0:1]
	s_waitcnt lgkmcnt(0)
	v_mov_b32_e32 v0, v244
	s_barrier
	s_cmpk_gt_i32 s2, 0xff
	v_readfirstlane_b32 s0, v0
	s_cbranch_scc1 .LBB0_647
	s_ashr_i32 s3, s0, 6
	s_cmp_gt_i32 s3, 5
	s_cselect_b32 s98, 1, 0
	s_xor_b32 s3, s3, s98
	v_writelane_b32 v254, s88, 39
	s_add_u32 s0, s58, 0x1b000000
	v_writelane_b32 v254, s0, 40
	s_addc_u32 s0, s59, 0
	v_writelane_b32 v254, s0, 41
	s_add_u32 s0, s58, 0x1b000200
	v_writelane_b32 v254, s0, 42
	s_addc_u32 s0, s59, 0
	v_writelane_b32 v254, s0, 43
	s_add_u32 s0, s58, 0x1b000400
	v_writelane_b32 v254, s0, 44
	s_addc_u32 s0, s59, 0
	s_cmp_eq_u32 s3, 2
	s_cselect_b64 s[64:65], -1, 0
	s_cmp_lg_u32 s3, 2
	v_writelane_b32 v254, s0, 45
	s_cselect_b64 s[74:75], -1, 0
	s_cmp_eq_u32 s3, 3
	s_movk_i32 s0, 0x80
	s_cselect_b32 s0, s0, 0xc0
	v_lshlrev_b32_e32 v1, 2, v0
	v_writelane_b32 v254, s0, 46
	v_and_b32_e32 v122, 12, v1
	v_bfe_u32 v1, v0, 2, 4
	s_movk_i32 s0, 0x90
	v_mov_b32_e32 v2, 0x900
	v_mad_u32_u24 v124, v1, s0, 0
	v_mad_u32_u24 v125, v1, s0, v2
	s_movk_i32 s0, 0xff72
	v_mad_i32_i24 v129, v1, s0, v124
	s_movk_i32 s1, 0x8e
	v_mad_u32_u24 v130, v1, s1, v129
	v_mad_i32_i24 v131, v1, s0, v130
	v_mad_u32_u24 v132, v1, s1, v131
	v_mad_i32_i24 v133, v1, s0, v132
	v_and_b32_e32 v72, 31, v0
	s_add_i32 s0, 0, 0x11e00
	v_mad_u32_u24 v148, v72, 48, s0
	s_add_i32 s0, 0, 0x11800
	v_mad_u32_u24 v149, v72, 48, s0
	s_add_i32 s0, 0, 0x13400
	v_mad_u32_u24 v150, v72, 48, s0
	s_add_i32 s0, 0, 0x12e00
	s_cmp_lt_i32 s3, 2
	s_cselect_b64 s[84:85], -1, 0
	s_lshl_b32 s86, s3, 5
	s_ashr_i32 s87, s86, 31
	v_mad_u32_u24 v151, v72, 48, s0
	s_add_u32 s0, s58, 0x15000400
	v_writelane_b32 v254, s0, 47
	s_addc_u32 s0, s59, 0
	s_add_u32 s76, s58, 0x15000800
	s_addc_u32 s77, s59, 0
	s_cmp_lg_u32 s3, 6
	v_and_b32_e32 v73, 63, v0
	s_cselect_b64 s[90:91], -1, 0
	s_cmp_eq_u32 s3, 6
	v_cmp_gt_u32_e64 s[12:13], 32, v73
	v_writelane_b32 v254, s0, 48
	s_cselect_b64 s[0:1], -1, 0
	v_lshlrev_b32_e32 v155, 2, v72
	s_add_i32 s40, 0, 0x11400
	s_add_i32 s4, 0, 0x12a00
	v_add_u32_e32 v159, s4, v155
	s_and_b64 s[4:5], s[0:1], s[12:13]
	v_writelane_b32 v254, s40, 49
	s_add_i32 s0, 0, 0x11430
	v_writelane_b32 v254, s0, 50
	s_add_i32 s0, 0, 0x117b0
	v_writelane_b32 v254, s0, 51
	s_add_i32 s0, 0, 0x11770
	v_writelane_b32 v254, s0, 52
	s_add_i32 s0, 0, 0x11730
	v_writelane_b32 v254, s0, 53
	s_add_i32 s0, 0, 0x11420
	v_writelane_b32 v254, s0, 54
	s_add_i32 s0, 0, 0x116f0
	v_writelane_b32 v254, s0, 55
	s_add_i32 s0, 0, 0x116b0
	v_writelane_b32 v254, s0, 56
	s_add_i32 s0, 0, 0x116a0
	v_writelane_b32 v254, s0, 57
	s_add_i32 s0, 0, 0x11670
	v_writelane_b32 v254, s0, 58
	s_add_i32 s0, 0, 0x11660
	v_writelane_b32 v254, s0, 59
	s_add_i32 s0, 0, 0x11630
	v_writelane_b32 v254, s0, 60
	s_add_i32 s0, 0, 0x11620
	v_writelane_b32 v254, s0, 61
	s_add_i32 s0, 0, 0x11410
	v_writelane_b32 v254, s0, 62
	s_add_i32 s0, 0, 0x115f0
	v_writelane_b32 v254, s0, 63
	s_add_i32 s0, 0, 0x115e0
	v_mul_u32_u24_e32 v123, 0x90, v1
	v_writelane_b32 v255, s0, 0
	s_add_i32 s0, 0, 0x115b0
	v_writelane_b32 v255, s0, 1
	s_add_i32 s0, 0, 0x115a0
	v_writelane_b32 v255, s0, 2
	s_add_i32 s0, 0, 0x11590
	v_lshlrev_b32_e32 v127, 1, v1
	v_cmp_eq_u32_e64 s[14:15], 15, v1
	v_bfe_u32 v1, v0, 5, 1
	v_and_b32_e32 v0, 15, v0
	v_writelane_b32 v255, s0, 3
	s_add_i32 s0, 0, 0x11570
	v_cmp_eq_u32_e32 vcc, 15, v0
	v_writelane_b32 v255, s0, 4
	s_add_i32 s0, 0, 0x11560
	v_cndmask_b32_e64 v161, 0, 1.0, vcc
	v_cmp_eq_u32_e32 vcc, 14, v0
	v_writelane_b32 v255, s0, 5
	s_add_i32 s0, 0, 0x11550
	v_cndmask_b32_e64 v162, 0, 1.0, vcc
	v_cmp_eq_u32_e32 vcc, 13, v0
	v_writelane_b32 v255, s0, 6
	s_add_i32 s0, 0, 0x11530
	v_cndmask_b32_e64 v163, 0, 1.0, vcc
	v_cmp_eq_u32_e32 vcc, 12, v0
	v_writelane_b32 v255, s0, 7
	s_add_i32 s0, 0, 0x11520
	v_cndmask_b32_e64 v164, 0, 1.0, vcc
	v_cmp_eq_u32_e32 vcc, 11, v0
	v_writelane_b32 v255, s0, 8
	s_add_i32 s0, 0, 0x11510
	v_cndmask_b32_e64 v165, 0, 1.0, vcc
	v_cmp_eq_u32_e32 vcc, 10, v0
	v_writelane_b32 v255, s0, 9
	s_add_i32 s0, 0, 0x114f0
	v_cndmask_b32_e64 v166, 0, 1.0, vcc
	v_cmp_eq_u32_e32 vcc, 9, v0
	v_writelane_b32 v255, s0, 10
	s_add_i32 s0, 0, 0x114e0
	v_cndmask_b32_e64 v167, 0, 1.0, vcc
	v_cmp_eq_u32_e32 vcc, 8, v0
	v_writelane_b32 v255, s0, 11
	s_add_i32 s0, 0, 0x114d0
	v_cndmask_b32_e64 v168, 0, 1.0, vcc
	v_cmp_eq_u32_e32 vcc, 7, v0
	v_writelane_b32 v255, s0, 12
	s_add_i32 s0, 0, 0x114b0
	v_cndmask_b32_e64 v169, 0, 1.0, vcc
	v_cmp_eq_u32_e32 vcc, 6, v0
	v_writelane_b32 v255, s0, 13
	s_add_i32 s0, 0, 0x114a0
	v_cndmask_b32_e64 v170, 0, 1.0, vcc
	v_cmp_eq_u32_e32 vcc, 5, v0
	v_writelane_b32 v255, s0, 14
	s_add_i32 s0, 0, 0x11490
	v_cndmask_b32_e64 v171, 0, 1.0, vcc
	v_cmp_eq_u32_e32 vcc, 4, v0
	v_writelane_b32 v255, s0, 15
	s_add_i32 s0, 0, 0x11480
	v_lshlrev_b32_e32 v138, 2, v1
	v_add_u32_e32 v2, -15, v72
	v_cmp_gt_u32_e64 s[16:17], 16, v72
	v_cndmask_b32_e64 v172, 0, 1.0, vcc
	v_cmp_eq_u32_e32 vcc, 3, v0
	v_writelane_b32 v255, s0, 16
	s_add_i32 s0, 0, 0x11470
	v_or_b32_e32 v139, 1, v138
	v_or_b32_e32 v140, 2, v138
	v_or_b32_e32 v141, 3, v138
	v_or_b32_e32 v142, 8, v138
	v_or_b32_e32 v143, 9, v138
	v_or_b32_e32 v144, 10, v138
	v_or_b32_e32 v145, 11, v138
	v_cndmask_b32_e64 v2, v2, v72, s[16:17]
	v_cndmask_b32_e64 v173, 0, 1.0, vcc
	v_cmp_eq_u32_e32 vcc, 2, v0
	v_writelane_b32 v255, s0, 17
	s_add_i32 s0, 0, 0x11460
	v_cmp_lt_u32_e64 s[20:21], v138, v2
	v_cmp_lt_u32_e64 s[22:23], v139, v2
	v_cmp_lt_u32_e64 s[24:25], v140, v2
	v_cmp_lt_u32_e64 s[26:27], v141, v2
	v_cmp_lt_u32_e64 s[28:29], v142, v2
	v_cmp_lt_u32_e64 s[30:31], v143, v2
	v_cmp_lt_u32_e64 s[34:35], v144, v2
	v_cmp_lt_u32_e64 s[36:37], v145, v2
	v_or_b32_e32 v2, s86, v72
	v_cndmask_b32_e64 v174, 0, 1.0, vcc
	v_cmp_eq_u32_e32 vcc, 1, v0
	v_writelane_b32 v255, s0, 18
	s_add_i32 s0, 0, 0x11450
	v_lshlrev_b32_e32 v134, 4, v1
	v_mul_u32_u24_e32 v135, 0x90, v72
	v_mul_lo_u32 v152, v2, 48
	v_or_b32_e32 v2, 32, v73
	v_cndmask_b32_e64 v175, 0, 1.0, vcc
	v_cmp_eq_u32_e32 vcc, 0, v0
	v_mad_u32_u24 v177, v72, 48, s40
	v_writelane_b32 v255, s0, 19
	s_add_i32 s0, 0, 0x11440
	v_mbcnt_lo_u32_b32 v0, -1, 0
	v_cmp_gt_u32_e64 s[6:7], 4, v73
	v_cmp_gt_u32_e64 s[8:9], 8, v73
	v_cmp_gt_u32_e64 s[10:11], 16, v73
	s_mov_b32 s82, 0
	v_add_u32_e32 v126, 0x900, v124
	v_or_b32_e32 v128, 32, v127
	v_lshlrev_b32_e32 v136, 3, v1
	v_mul_u32_u24_e32 v137, 48, v72
	v_lshlrev_b32_e32 v146, 1, v142
	v_add3_u32 v147, 0, v135, v134
	v_cmp_lt_u32_e64 s[18:19], 15, v72
	v_mov_b32_e32 v75, 0
	s_movk_i32 s88, 0x50
	v_mul_u32_u24_e32 v153, 0x50, v72
	v_mul_u32_u24_e32 v154, 0x50, v2
	v_add_u32_e32 v156, s40, v155
	v_lshlrev_b32_e32 v157, 8, v1
	v_lshlrev_b32_e32 v158, 6, v142
	v_mul_u32_u24_e32 v160, 48, v73
	v_cndmask_b32_e64 v176, 0, 1.0, vcc
	v_cmp_lt_u32_e64 s[38:39], 15, v73
	v_add_u32_e32 v178, v177, v134
	s_add_i32 s78, s3, -3
	s_movk_i32 s89, 0x200
	s_movk_i32 s79, 0xc00
	v_writelane_b32 v255, s0, 20
	v_mbcnt_hi_u32_b32 v179, -1, v0
	v_mov_b32_e32 v180, 0xa0
	v_mov_b32_e32 v181, 0xf0
	s_mov_b32 s80, s2
	s_branch .LBB0_530

; template <bool RWKV> __device__ __forceinline__ void scan_load_issue(ScanLd& L, const ScanSrc& S, int chunk, int lt) {
;     const int lw = lt >> 6, lane = lt & 63, sl = lane >> 2, col = 16 * lw + 4 * (lane & 3), s = chunk * SC_CH + sl; const size_t tok = (size_t)(S.tokbase + (S.rev ? T_SEQ - 1 - s : s));
;     L.rd = *(const u32x2*)(S.v[0] + tok * S.ld[0] + col); L.rk = *(const u32x2*)(S.v[1] + tok * S.ld[1] + col); L.rr = *(const u32x2*)(S.v[4] + tok * S.ld[4] + col); L.rv = *(const u32x2*)(S.v[5] + tok * S.ld[5] + col);
; template <bool RWKV> __device__ __forceinline__ void scan_item(LAS unsigned char* lds, const ScanSrc& S, int wid, int lane) {
;     f32x16 T[2];
; #pragma unroll
;     for (int a = 0; a < 2; ++a)
; #pragma unroll
;         for (int i = 0; i < 16; ++i) T[a][i] = 0.f;
;     const bool is_ld = (wid == 4) | (wid == 5) | (wid == 3) | (wid == 7); const bool is_prep = wid == 2;
;     const int lt = (wid == 4 ? 0 : wid == 5 ? 64 : wid == 3 ? 128 : 192) + lane;
;     ScanLd L;
;     constexpr int NCH = T_SEQ / SC_CH;
;     ...
;     const bool is_inv = wid == 6;
;     if (is_ld) { scan_load_issue<RWKV>(L, S, 0, lt); scan_load_finish<RWKV>(lds, L, lt); scan_load_issue<RWKV>(L, S, 1, lt); scan_load_finish<RWKV>(lds + SC_BUF, L, lt);
;                  scan_load_issue<RWKV>(L, S, 2, lt); scan_load_finish<RWKV>(lds + 2 * SC_BUF, L, lt); scan_load_issue<RWKV>(L, S, 3, lt); }
.LBB0_553:
	s_lshl_b32 s0, s69, 25
	s_add_u32 s0, s56, s0
	s_addc_u32 s1, s57, 0
	s_lshl_b32 s67, s70, 1
	s_add_u32 s0, s0, s67
	s_addc_u32 s1, s1, 0
	s_add_u32 s67, s0, s71
	s_addc_u32 s70, s1, 0
	s_lshr_b32 s0, s68, 2
	v_or_b32_e32 v0, s0, v122
	s_lshl_b64 s[0:1], s[86:87], 1
	v_lshlrev_b32_e32 v74, 1, v16
	s_add_u32 s0, s67, s0
	s_waitcnt vmcnt(5)
	v_lshl_add_u64 v[76:77], s[40:41], 0, v[74:75]
	s_waitcnt vmcnt(4)
	v_lshl_add_u64 v[78:79], s[42:43], 0, v[74:75]
	s_waitcnt vmcnt(3)
	v_lshl_add_u64 v[80:81], s[94:95], 0, v[74:75]
	s_waitcnt vmcnt(2)
	v_lshl_add_u64 v[82:83], s[60:61], 0, v[74:75]
	s_addc_u32 s1, s70, s1
	v_lshlrev_b32_e32 v74, 1, v72
	v_lshlrev_b32_e32 v102, 1, v0
	v_mul_u32_u24_e32 v103, 0x50, v0
	v_mul_u32_u24_e32 v104, 48, v0
	v_mad_u32_u24 v105, v0, s88, s88
	v_mad_u32_u24 v106, v0, s88, v180
	v_mad_u32_u24 v107, v0, s88, v181
	v_lshlrev_b32_e32 v108, 2, v0
	v_lshl_add_u64 v[0:1], s[0:1], 0, v[74:75]
	s_mov_b64 s[0:1], 0x4000000
	s_cmp_eq_u32 s69, 0
	s_waitcnt lgkmcnt(0)
	s_barrier
	s_waitcnt vmcnt(1)
	v_lshl_add_u64 v[84:85], v[0:1], 0, s[0:1]
	s_cselect_b64 s[0:1], -1, 0
	v_add_u32_e32 v0, s68, v73
	s_waitcnt lgkmcnt(0)
	s_barrier
	s_and_b64 s[40:41], s[0:1], exec
	v_bfe_u32 v0, v0, 2, 4
	s_cselect_b32 s40, s89, 0xfffffe00
	v_or_b32_e32 v109, 64, v0
	v_sub_u32_e32 v110, 0, v0
	v_mov_b32_e32 v0, 0
	s_mov_b32 s67, 0
	s_waitcnt vmcnt(0)
	v_mul_hi_i32_i24_e32 v87, s40, v138
	v_mul_i32_i24_e32 v86, s40, v138
	v_mul_hi_i32_i24_e32 v89, s40, v139
	v_mul_i32_i24_e32 v88, s40, v139
	v_mul_hi_i32_i24_e32 v91, s40, v140
	v_mul_i32_i24_e32 v90, s40, v140
	v_mul_hi_i32_i24_e32 v93, s40, v141
	v_mul_i32_i24_e32 v92, s40, v141
	v_mul_hi_i32_i24_e32 v95, s40, v142
	v_mul_i32_i24_e32 v94, s40, v142
	v_mul_hi_i32_i24_e32 v97, s40, v143
	v_mul_i32_i24_e32 v96, s40, v143
	v_mul_hi_i32_i24_e32 v99, s40, v144
	v_mul_i32_i24_e32 v98, s40, v144
	v_mul_hi_i32_i24_e32 v101, s40, v145
	v_mul_i32_i24_e32 v100, s40, v145
	s_movk_i32 s68, 0xfbf
	s_mov_b32 s69, 0
	s_mov_b32 s72, 0
	s_mov_b32 s70, 0
	v_mov_b32_e32 v1, v0
	v_mov_b32_e32 v2, v0
	v_mov_b32_e32 v3, v0
	v_mov_b32_e32 v4, v0
	v_mov_b32_e32 v5, v0
	v_mov_b32_e32 v6, v0
	v_mov_b32_e32 v7, v0
	v_mov_b32_e32 v8, v0
	v_mov_b32_e32 v9, v0
	v_mov_b32_e32 v10, v0
	v_mov_b32_e32 v11, v0
	v_mov_b32_e32 v12, v0
	v_mov_b32_e32 v13, v0
	v_mov_b32_e32 v14, v0
	v_mov_b32_e32 v15, v0
	v_mov_b32_e32 v16, v0
	v_mov_b32_e32 v17, v0
	v_mov_b32_e32 v18, v0
	v_mov_b32_e32 v19, v0
	v_mov_b32_e32 v20, v0
	v_mov_b32_e32 v21, v0
	v_mov_b32_e32 v22, v0
	v_mov_b32_e32 v23, v0
	v_mov_b32_e32 v24, v0
	v_mov_b32_e32 v25, v0
	v_mov_b32_e32 v26, v0
	v_mov_b32_e32 v27, v0
	v_mov_b32_e32 v28, v0
	v_mov_b32_e32 v29, v0
	v_mov_b32_e32 v30, v0
	v_mov_b32_e32 v31, v0
	v_and_b32_e32 v251, 3, v73
	v_and_b32_e32 v252, 48, v73
	v_add_u32_e32 v251, v251, v252
	v_add_u32_e32 v251, -4, v251
	v_and_b32_e32 v253, 16, v73
	v_cmp_ne_u32_e32 vcc, 0, v253
	v_and_b32_e32 v252, 3, v73
	v_add_u32_e32 v252, 28, v252
	v_cndmask_b32_e32 v251, v73, v251, vcc
	v_cndmask_b32_e64 v253, 0, 1.0, vcc
	v_cmp_lt_u32_e32 vcc, 31, v73
	v_lshlrev_b32_e32 v251, 2, v251
	v_lshlrev_b32_e32 v252, 2, v252
	v_cndmask_b32_e64 v245, 0, 1.0, vcc
	v_add_u32_e32 v248, v123, v102
	v_add_u32_e32 v249, v103, v127
	v_add_u32_e32 v250, v104, v127
	v_add_u32_e32 v33, 0xfbf, v110
	v_cndmask_b32_e64 v32, v33, v109, s[0:1]
	v_add_u32_e32 v32, s66, v32
	v_mov_b32_e32 v33, 0
	v_lshlrev_b64 v[34:35], 10, v[32:33]
	v_lshlrev_b64 v[36:37], 11, v[32:33]
	v_lshl_add_u64 v[234:235], v[76:77], 0, v[34:35]
	v_lshl_add_u64 v[236:237], v[78:79], 0, v[36:37]
	v_lshl_add_u64 v[238:239], v[80:81], 0, v[36:37]
	v_lshl_add_u64 v[240:241], v[82:83], 0, v[36:37]
	s_and_b64 s[40:41], s[0:1], exec
	s_mov_b32 s98, 0x4000
	s_cselect_b32 s98, s98, 0xffffc000
	s_cselect_b32 s99, 0, -1
	s_mov_b32 s100, 0x8000
	s_cselect_b32 s100, s100, 0xffff8000
	s_cselect_b32 s101, 0, -1
	s_branch .LBB0_556

; template <bool RWKV> __device__ __forceinline__ void scan_item(LAS unsigned char* lds, const ScanSrc& S, int wid, int lane) {
;     ...
;     for (int c = 0; c < NCH; ++c) {
;         const int i1 = i0 == 2 ? 0 : i0 + 1, i2 = i1 == 2 ? 0 : i1 + 1;
;         if (is_ld) {
;             if (c + 3 < NCH) scan_load_finish<RWKV>(lds + ((b0 + 3) & 3) * SC_BUF, L, lt);
;             if (c + 4 < NCH) scan_load_issue<RWKV>(L, S, c + 4, lt); }
;         else if (is_prep) { if (c + 2 < NCH) scan_prep_m1<RWKV>(lds + ((b0 + 2) & 3) * SC_BUF, lds + SC_IMG + i2 * SW_SIZE, lane); }
;         else if (is_inv) { if (c + 1 < NCH) scan_prep_inv<RWKV>(lds + SC_IMG + i1 * SW_SIZE, lane); }
;         else if (wid < 2) scan_chunk<RWKV>(lds + b0 * SC_BUF, lds + SC_IMG + i0 * SW_SIZE, T, S, c, wid, lane);
.LBB0_556:
	s_add_i32 s40, s72, 1
	s_cmp_lg_u32 s72, 2
	s_cselect_b32 s71, s40, 0
	s_cmp_lt_i32 s3, 2
	s_cbranch_scc1 .Lgl_compute
	s_cmp_lt_i32 s3, 7
	s_cbranch_scc1 .LBB0_558
	s_cmp_lg_u32 s3, 7
	s_mov_b64 s[40:41], -1
	s_cselect_b64 s[42:43], -1, 0
	s_cbranch_execz .LBB0_559
	s_branch .LBB0_560

; template <bool RWKV> __device__ __forceinline__ void scan_item(LAS unsigned char* lds, const ScanSrc& S, int wid, int lane) {
;     ...
;     for (int c = 0; c < NCH; ++c) {
;         const int i1 = i0 == 2 ? 0 : i0 + 1, i2 = i1 == 2 ? 0 : i1 + 1;
;         if (is_ld) {
;             if (c + 3 < NCH) scan_load_finish<RWKV>(lds + ((b0 + 3) & 3) * SC_BUF, L, lt);
;             if (c + 4 < NCH) scan_load_issue<RWKV>(L, S, c + 4, lt); }
;         else if (is_prep) { if (c + 2 < NCH) scan_prep_m1<RWKV>(lds + ((b0 + 2) & 3) * SC_BUF, lds + SC_IMG + i2 * SW_SIZE, lane); }
;         else if (is_inv) { if (c + 1 < NCH) scan_prep_inv<RWKV>(lds + SC_IMG + i1 * SW_SIZE, lane); }
;         else if (wid < 2) scan_chunk<RWKV>(lds + b0 * SC_BUF, lds + SC_IMG + i0 * SW_SIZE, T, S, c, wid, lane);
.LBB0_562:
	s_mov_b64 s[40:41], -1
	s_and_b64 vcc, exec, s[74:75]
	s_cbranch_vccz .LBB0_566
.LBB0_565:
	s_mov_b64 s[40:41], 0

; template <bool RWKV> __device__ __forceinline__ void scan_load_issue(ScanLd& L, const ScanSrc& S, int chunk, int lt) {
;     const int lw = lt >> 6, lane = lt & 63, sl = lane >> 2, col = 16 * lw + 4 * (lane & 3), s = chunk * SC_CH + sl; const size_t tok = (size_t)(S.tokbase + (S.rev ? T_SEQ - 1 - s : s));
;     L.rd = *(const u32x2*)(S.v[0] + tok * S.ld[0] + col); L.rk = *(const u32x2*)(S.v[1] + tok * S.ld[1] + col); L.rr = *(const u32x2*)(S.v[4] + tok * S.ld[4] + col); L.rv = *(const u32x2*)(S.v[5] + tok * S.ld[5] + col);
;     L.rkk = L.rk; L.rnb = L.rk;
;     if (RWKV) { L.rkk = *(const u32x2*)(S.v[2] + tok * S.ld[2] + col); L.rnb = *(const u32x2*)(S.v[3] + tok * S.ld[3] + col); }
; }
; template <bool RWKV> __device__ __forceinline__ void scan_load_finish(LAS unsigned char* buf, const ScanLd& L, int lt) {
;     const int lw = lt >> 6, lane = lt & 63, sl = lane >> 2, col = 16 * lw + 4 * (lane & 3);
;     float d[4], c[4], k[4], r[4], v[4], kk[4], nb[4];
;     unpack4(L.rd, d); unpack4(L.rk, k); unpack4(L.rr, r); unpack4(L.rv, v); unpack4(L.rkk, kk); unpack4(L.rnb, nb);
; #pragma unroll
;     for (int i = 0; i < 4; ++i) c[i] = d[i];
; #pragma unroll
;     for (int dl = 4; dl < 64; dl <<= 1)
; #pragma unroll
;         for (int i = 0; i < 4; ++i) { const float t = __shfl_up(c[i], dl); c[i] += (lane >= dl) ? t : 0.f; }
;     float o1[4], o2[4], o3[4], o4[4]; f32x4 we;
; #pragma unroll
;     for (int i = 0; i < 4; ++i) { const float W = __expf(-c[i]), iW = __expf(c[i]), Wp = __expf(d[i] - c[i]); o1[i] = RWKV ? kk[i] * Wp : 0.f; o2[i] = RWKV ? nb[i] * iW : 0.f; o3[i] = k[i] * iW; o4[i] = r[i] * W; we[i] = W; }
;     u32x2 w;
;     w.x = cvt2(o1[0], o1[1]); w.y = cvt2(o1[2], o1[3]); *(LAS u32x2*)(buf + SB_XA + sl * 144 + col * 2) = w;
;     w.x = cvt2(o4[0], o4[1]); w.y = cvt2(o4[2], o4[3]); *(LAS u32x2*)(buf + SB_XA + (16 + sl) * 144 + col * 2) = w;
;     w.x = cvt2(o2[0], o2[1]); w.y = cvt2(o2[2], o2[3]); *(LAS u32x2*)(buf + SB_XB + sl * 144 + col * 2) = w;
;     w.x = cvt2(o3[0], o3[1]); w.y = cvt2(o3[2], o3[3]); *(LAS u32x2*)(buf + SB_XB + (16 + sl) * 144 + col * 2) = w;
; #pragma unroll
;     for (int i = 0; i < 4; ++i) {
;         *(LAS unsigned short*)(buf + SB_XBT + (col + i) * 80 + sl * 2) = (unsigned short)(cvt2(o2[i], 0.f) & 0xffffu);
.LBB0_571:
	s_cmpk_gt_u32 s69, 0xfc
	s_cbranch_scc1 .LBB0_555
	s_add_i32 s40, s70, -1
	s_and_b32 s40, s40, 3
	s_mulk_i32 s40, 0x4500
	v_add_u32_e32 v190, s40, v250
	s_waitcnt vmcnt(0)
	ds_write_b16 v190, v70 offset:14336
	ds_write_b16_d16_hi v190, v70 offset:14384
	ds_write_b16 v190, v71 offset:14432
	ds_write_b16_d16_hi v190, v71 offset:14480
	v_lshlrev_b32_e32 v32, 16, v64
	v_and_b32_e32 v33, 0xffff0000, v64
	v_lshlrev_b32_e32 v34, 16, v65
	v_and_b32_e32 v35, 0xffff0000, v65
	v_lshlrev_b32_e32 v36, 16, v66
	v_and_b32_e32 v37, 0xffff0000, v66
	v_lshlrev_b32_e32 v38, 16, v67
	v_and_b32_e32 v39, 0xffff0000, v67
	v_lshlrev_b32_e32 v40, 16, v68
	v_and_b32_e32 v41, 0xffff0000, v68
	v_lshlrev_b32_e32 v42, 16, v69
	v_and_b32_e32 v43, 0xffff0000, v69
	s_cmpk_gt_u32 s69, 0xfb
	s_cbranch_scc1 .Lgl_ldfin
	global_load_dwordx2 v[64:65], v[234:235], off
	global_load_dwordx2 v[66:67], v[236:237], off
	global_load_dwordx2 v[68:69], v[238:239], off
	global_load_dwordx2 v[70:71], v[240:241], off
	v_lshl_add_u64 v[234:235], v[234:235], 0, s[98:99]
	v_lshl_add_u64 v[236:237], v[236:237], 0, s[100:101]
	v_lshl_add_u64 v[238:239], v[238:239], 0, s[100:101]
	v_lshl_add_u64 v[240:241], v[240:241], 0, s[100:101]
.Lgl_ldfin:
	v_mul_f32_e32 v52, 0x3fb8aa3b, v32
	v_mul_f32_e32 v53, 0x3fb8aa3b, v33
	v_mul_f32_e32 v54, 0x3fb8aa3b, v34
	v_mul_f32_e32 v55, 0x3fb8aa3b, v35
	v_add_f32_dpp v52, v52, v52 row_shr:4 row_mask:0xf bank_mask:0xf
	v_add_f32_dpp v53, v53, v53 row_shr:4 row_mask:0xf bank_mask:0xf
	v_add_f32_dpp v54, v54, v54 row_shr:4 row_mask:0xf bank_mask:0xf
	v_add_f32_dpp v55, v55, v55 row_shr:4 row_mask:0xf bank_mask:0xf
	v_add_f32_dpp v52, v52, v52 row_shr:8 row_mask:0xf bank_mask:0xf
	v_add_f32_dpp v53, v53, v53 row_shr:8 row_mask:0xf bank_mask:0xf
	v_add_f32_dpp v54, v54, v54 row_shr:8 row_mask:0xf bank_mask:0xf
	v_add_f32_dpp v55, v55, v55 row_shr:8 row_mask:0xf bank_mask:0xf
	ds_bpermute_b32 v60, v251, v52
	ds_bpermute_b32 v61, v251, v53
	ds_bpermute_b32 v62, v251, v54
	ds_bpermute_b32 v63, v251, v55
	s_waitcnt lgkmcnt(0)
	v_fmac_f32_e32 v52, v60, v253
	v_fmac_f32_e32 v53, v61, v253
	v_fmac_f32_e32 v54, v62, v253
	v_fmac_f32_e32 v55, v63, v253
	ds_bpermute_b32 v60, v252, v52
	ds_bpermute_b32 v61, v252, v53
	ds_bpermute_b32 v62, v252, v54
	ds_bpermute_b32 v63, v252, v55
	s_waitcnt lgkmcnt(0)
	v_fmac_f32_e32 v52, v60, v245
	v_fmac_f32_e32 v53, v61, v245
	v_fmac_f32_e32 v54, v62, v245
	v_fmac_f32_e32 v55, v63, v245
	v_exp_f32_e64 v194, -v52
	v_exp_f32_e64 v195, -v53
	v_exp_f32_e64 v196, -v54
	v_exp_f32_e64 v197, -v55
	v_exp_f32_e32 v198, v52
	v_exp_f32_e32 v199, v53
	v_exp_f32_e32 v200, v54
	v_exp_f32_e32 v201, v55
	v_add_u32_e32 v191, s40, v248
	v_mov_b32_e32 v192, 0
	v_mov_b32_e32 v193, 0
	v_pk_mul_f32 v[208:209], v[194:195], v[40:41]
	v_pk_mul_f32 v[210:211], v[196:197], v[42:43]
	v_pk_mul_f32 v[204:205], v[198:199], v[36:37]
	v_pk_mul_f32 v[206:207], v[200:201], v[38:39]
	v_cvt_pk_bf16_f32 v218, v208, v209
	v_cvt_pk_bf16_f32 v219, v210, v211
	v_cvt_pk_bf16_f32 v216, v204, v205
	v_cvt_pk_bf16_f32 v217, v206, v207
	v_add_u32_e32 v220, 0x900, v191
	v_add_u32_e32 v221, s40, v249
	ds_write2st64_b64 v191, v[192:193], v[192:193] offset1:9
	ds_write2st64_b64 v220, v[218:219], v[216:217] offset1:9
	ds_write_b16 v221, v192 offset:9216
	ds_write_b16 v221, v192 offset:9296
	ds_write_b16 v221, v192 offset:9376
	ds_write_b16 v221, v192 offset:9456
	ds_write_b16 v221, v216 offset:9248
	ds_write_b16_d16_hi v221, v216 offset:9328
	ds_write_b16 v221, v217 offset:9408
	ds_write_b16_d16_hi v221, v217 offset:9488
	s_and_saveexec_b64 s[42:43], s[14:15]
	v_add_u32_e32 v222, s40, v108
	ds_write_b128 v222, v[194:197] offset:17408
	s_or_b64 exec, exec, s[42:43]
	s_branch .LBB0_555
; template <bool RWKV> __device__ __forceinline__ void scan_chunk(const LAS unsigned char* buf, const LAS unsigned char* img, f32x16 (&T)[2], const ScanSrc& S, int chunk, int w, int lane) {
;     const int r = lane & 31, h = lane >> 5;
;     f32x16 zero;
; #pragma unroll
;     for (int i = 0; i < 16; ++i) zero[i] = 0.f;
;     const bf16x8 vb = *(const LAS bf16x8*)(buf + SB_VT + (32 * w + r) * 48 + 16 * h);
;     f32x16 ry = zero, ry2 = zero;
; #pragma unroll
;     for (int kb = 0; kb < 2; ++kb) {
;         const bf16x8 b0 = pack8r(T[0][8 * kb], T[0][8 * kb + 1], T[0][8 * kb + 2], T[0][8 * kb + 3], T[0][8 * kb + 4], T[0][8 * kb + 5], T[0][8 * kb + 6], T[0][8 * kb + 7]);
;         const bf16x8 b1 = pack8r(T[1][8 * kb], T[1][8 * kb + 1], T[1][8 * kb + 2], T[1][8 * kb + 3], T[1][8 * kb + 4], T[1][8 * kb + 5], T[1][8 * kb + 6], T[1][8 * kb + 7]);
;         ry = MFMA32(lds_aperm(buf + SB_XA + r * 144 + (16 * kb) * 2, h), b0, ry);
;         ry2 = MFMA32(lds_aperm(buf + SB_XA + r * 144 + (32 + 16 * kb) * 2, h), b1, ry2); }
;     { const bf16x8 a = *(const LAS bf16x8*)(img + SW_HT + r * 48 + 16 * h); ry = MFMA32(a, vb, ry); }
; #pragma unroll
;     for (int i = 0; i < 16; ++i) ry[i] += ry2[i];
;     bf16x8 ub;
;     if (RWKV) {
;         const bf16x8 rb = pack8r(ry[0], ry[1], ry[2], ry[3], ry[4], ry[5], ry[6], ry[7]);
;         const f32x16 ua = MFMA32(lds_aperm(img + SW_TIT + r * 48, h), rb, zero);
;         ub = pack8r(ua[0], ua[1], ua[2], ua[3], ua[4], ua[5], ua[6], ua[7]);
;         ry = MFMA32(lds_aperm(img + SW_GYT + r * 48, h), ub, ry);
;     }
;     {
;         const int s0 = chunk * SC_CH; const long tok0 = (long)S.tokbase + (S.rev ? T_SEQ - 1 - s0 : s0), dstep = S.rev ? -512 : 512;
;         bf16_t* op = S.out + tok0 * 512 + 32 * w + r;
; #pragma unroll
;         for (int q = 8; q < 16; ++q) { const int s = (q & 3) + 8 * ((q >> 2) - 2) + 4 * h; op[s * dstep] = (bf16_t)(cvt2(ry[q], 0.f) & 0xffffu); }
;     }
; #pragma unroll
;     for (int jt = 0; jt < 2; ++jt) {
;         if (RWKV) T[jt] = MFMA32(lds_aperm(buf + SB_XBT + (32 * jt + r) * 80, h), ub, T[jt]);
;         { const bf16x8 a = *(const LAS bf16x8*)(buf + SB_XBT + (32 * jt + r) * 80 + 32 + 16 * h); T[jt] = MFMA32(a, vb, T[jt]); }
; #pragma unroll
;         for (int g = 0; g < 4; ++g) { const f32x4 we = *(const LAS f32x4*)(buf + SB_WE + (32 * jt + 8 * g + 4 * h) * 4);
; #pragma unroll
.Lgl_compute:
	s_mul_i32 s40, s70, 0x4500
	s_mul_i32 s41, s72, 0x1600
	v_add3_u32 v74, s40, v135, v136
	v_add_u32_e32 v249, s40, v134
	ds_read2_b64 v[32:35], v74 offset1:2
	ds_read2_b64 v[36:39], v74 offset0:4 offset1:6
	v_add_u32_e32 v250, v249, v152
	ds_read2_b64 v[40:43], v74 offset0:8 offset1:10
	ds_read2_b64 v[44:47], v74 offset0:12 offset1:14
	ds_read_b128 v[48:51], v250 offset:14336
	v_add_u32_e32 v250, s41, v178
	v_cvt_pk_bf16_f32 v112, v0, v1
	v_cvt_pk_bf16_f32 v113, v2, v3
	v_cvt_pk_bf16_f32 v114, v4, v5
	v_cvt_pk_bf16_f32 v115, v6, v7
	ds_read_b128 v[52:55], v250 offset:1024
	v_add_u32_e32 v250, v249, v153
	ds_read_b128 v[56:59], v250 offset:9248
	v_add_u32_e32 v250, v249, v154
	ds_read_b128 v[60:63], v250 offset:9248
	v_cvt_pk_bf16_f32 v116, v8, v9
	v_cvt_pk_bf16_f32 v117, v10, v11
	v_cvt_pk_bf16_f32 v118, v12, v13
	v_cvt_pk_bf16_f32 v119, v14, v15
	v_cvt_pk_bf16_f32 v182, v16, v17
	v_cvt_pk_bf16_f32 v183, v18, v19
	v_cvt_pk_bf16_f32 v184, v20, v21
	v_cvt_pk_bf16_f32 v185, v22, v23
	v_cvt_pk_bf16_f32 v186, v24, v25
	v_cvt_pk_bf16_f32 v187, v26, v27
	v_cvt_pk_bf16_f32 v188, v28, v29
	v_cvt_pk_bf16_f32 v189, v30, v31
	s_waitcnt lgkmcnt(7)
	v_mfma_f32_32x32x16_bf16 v[190:205], v[32:35], v[112:115], 0
	s_waitcnt lgkmcnt(6)
	v_mfma_f32_32x32x16_bf16 v[190:205], v[36:39], v[116:119], v[190:205]
	s_waitcnt lgkmcnt(5)
	v_mfma_f32_32x32x16_bf16 v[190:205], v[40:43], v[182:185], v[190:205]
	s_waitcnt lgkmcnt(4)
	v_mfma_f32_32x32x16_bf16 v[190:205], v[44:47], v[186:189], v[190:205]
	s_waitcnt lgkmcnt(2)
	v_mfma_f32_32x32x16_bf16 v[190:205], v[52:55], v[48:51], v[190:205]
	s_waitcnt lgkmcnt(1)
	v_mfma_f32_32x32x16_bf16 v[0:15], v[56:59], v[48:51], v[0:15]
	s_waitcnt lgkmcnt(0)
	v_mfma_f32_32x32x16_bf16 v[16:31], v[60:63], v[48:51], v[16:31]
	ds_read_b128 v[32:35], v249 offset:17408
	ds_read_b128 v[36:39], v249 offset:17440
	ds_read_b128 v[40:43], v249 offset:17472
	ds_read_b128 v[44:47], v249 offset:17504
	ds_read_b128 v[112:115], v249 offset:17536
	ds_read_b128 v[116:119], v249 offset:17568
	ds_read_b128 v[182:185], v249 offset:17600
	ds_read_b128 v[186:189], v249 offset:17632
	s_add_i32 s42, s68, 64
	s_and_b64 s[40:41], s[0:1], exec
	s_cselect_b32 s40, s67, s42
	s_add_i32 s40, s40, s66
	s_mov_b32 s41, s82
	s_lshl_b64 s[40:41], s[40:41], 10
	v_lshl_add_u64 v[222:223], v[84:85], 0, s[40:41]
	v_lshl_add_u64 v[224:225], v[86:87], 1, v[222:223]
	v_lshl_add_u64 v[226:227], v[88:89], 1, v[222:223]
	v_lshl_add_u64 v[228:229], v[90:91], 1, v[222:223]
	v_lshl_add_u64 v[230:231], v[92:93], 1, v[222:223]
	v_lshl_add_u64 v[232:233], v[94:95], 1, v[222:223]
	v_lshl_add_u64 v[234:235], v[96:97], 1, v[222:223]
	v_lshl_add_u64 v[236:237], v[98:99], 1, v[222:223]
	v_lshl_add_u64 v[238:239], v[100:101], 1, v[222:223]
	v_cvt_pk_bf16_f32 v240, v198, v198
	global_store_short v[224:225], v240, off
	v_cvt_pk_bf16_f32 v241, v199, v199
	global_store_short v[226:227], v241, off
	v_cvt_pk_bf16_f32 v242, v200, v200
	global_store_short v[228:229], v242, off
	v_cvt_pk_bf16_f32 v243, v201, v201
	global_store_short v[230:231], v243, off
	v_cvt_pk_bf16_f32 v245, v202, v202
	global_store_short v[232:233], v245, off
	v_cvt_pk_bf16_f32 v246, v203, v203
	global_store_short v[234:235], v246, off
	v_cvt_pk_bf16_f32 v247, v204, v204
	global_store_short v[236:237], v247, off
	v_cvt_pk_bf16_f32 v248, v205, v205
	global_store_short v[238:239], v248, off
	s_waitcnt lgkmcnt(0)
	v_pk_mul_f32 v[0:1], v[0:1], v[32:33]
	v_pk_mul_f32 v[2:3], v[2:3], v[34:35]
	v_pk_mul_f32 v[4:5], v[4:5], v[36:37]
	v_pk_mul_f32 v[6:7], v[6:7], v[38:39]
	v_pk_mul_f32 v[8:9], v[8:9], v[40:41]
	v_pk_mul_f32 v[10:11], v[10:11], v[42:43]
	v_pk_mul_f32 v[12:13], v[12:13], v[44:45]
	v_pk_mul_f32 v[14:15], v[14:15], v[46:47]
	v_pk_mul_f32 v[16:17], v[16:17], v[112:113]
	v_pk_mul_f32 v[18:19], v[18:19], v[114:115]
	v_pk_mul_f32 v[20:21], v[20:21], v[116:117]
	v_pk_mul_f32 v[22:23], v[22:23], v[118:119]
	v_pk_mul_f32 v[24:25], v[24:25], v[182:183]
	v_pk_mul_f32 v[26:27], v[26:27], v[184:185]
	v_pk_mul_f32 v[28:29], v[28:29], v[186:187]
	v_pk_mul_f32 v[30:31], v[30:31], v[188:189]
	s_branch .LBB0_555

; template <bool RWKV> __device__ __forceinline__ void scan_load_issue(ScanLd& L, const ScanSrc& S, int chunk, int lt) {
;     const int lw = lt >> 6, lane = lt & 63, sl = lane >> 2, col = 16 * lw + 4 * (lane & 3), s = chunk * SC_CH + sl; const size_t tok = (size_t)(S.tokbase + (S.rev ? T_SEQ - 1 - s : s));
;     L.rd = *(const u32x2*)(S.v[0] + tok * S.ld[0] + col); L.rk = *(const u32x2*)(S.v[1] + tok * S.ld[1] + col); L.rr = *(const u32x2*)(S.v[4] + tok * S.ld[4] + col); L.rv = *(const u32x2*)(S.v[5] + tok * S.ld[5] + col);
;     L.rkk = L.rk; L.rnb = L.rk;
;     if (RWKV) { L.rkk = *(const u32x2*)(S.v[2] + tok * S.ld[2] + col); L.rnb = *(const u32x2*)(S.v[3] + tok * S.ld[3] + col); }
; template <bool RWKV> __device__ __forceinline__ void scan_item(LAS unsigned char* lds, const ScanSrc& S, int wid, int lane) {
;     f32x16 T[2];
; #pragma unroll
;     for (int a = 0; a < 2; ++a)
; #pragma unroll
;         for (int i = 0; i < 16; ++i) T[a][i] = 0.f;
;     const bool is_ld = (wid == 4) | (wid == 5) | (wid == 3) | (wid == 7); const bool is_prep = wid == 2;
;     const int lt = (wid == 4 ? 0 : wid == 5 ? 64 : wid == 3 ? 128 : 192) + lane;
;     ScanLd L;
;     constexpr int NCH = T_SEQ / SC_CH;
;     ...
;     const bool is_inv = wid == 6;
;     if (is_ld) { scan_load_issue<RWKV>(L, S, 0, lt); scan_load_finish<RWKV>(lds, L, lt); scan_load_issue<RWKV>(L, S, 1, lt); scan_load_finish<RWKV>(lds + SC_BUF, L, lt);
;                  scan_load_issue<RWKV>(L, S, 2, lt); scan_load_finish<RWKV>(lds + 2 * SC_BUF, L, lt); scan_load_issue<RWKV>(L, S, 3, lt); }
.LBB0_611:
	s_or_b64 exec, exec, s[72:73]
	s_lshl_b32 s72, s89, 25
	s_add_u32 s72, s56, s72
	s_addc_u32 s73, s57, 0
	s_add_u32 s72, s72, s93
	v_lshlrev_b32_e32 v74, 1, v20
	s_addc_u32 s73, s73, 0
	s_lshr_b32 s89, s81, 2
	v_lshl_add_u64 v[88:89], s[0:1], 0, v[74:75]
	s_lshl_b64 s[0:1], s[86:87], 1
	v_or_b32_e32 v0, s89, v122
	s_add_u32 s0, s72, s0
	v_lshlrev_b32_e32 v182, 1, v0
	v_mul_u32_u24_e32 v183, 0x50, v0
	v_mul_u32_u24_e32 v184, 48, v0
	v_mad_u32_u24 v185, v0, s88, s88
	v_mad_u32_u24 v186, v0, s88, v180
	v_mad_u32_u24 v187, v0, s88, v181
	v_lshlrev_b32_e32 v188, 2, v0
	v_lshl_add_u64 v[90:91], s[60:61], 0, v[74:75]
	v_lshl_add_u64 v[92:93], s[68:69], 0, v[74:75]
	v_lshl_add_u64 v[94:95], s[70:71], 0, v[74:75]
	v_lshl_add_u64 v[96:97], s[42:43], 0, v[74:75]
	v_lshl_add_u64 v[98:99], s[66:67], 0, v[74:75]
	s_addc_u32 s1, s73, s1
	v_lshlrev_b32_e32 v74, 1, v72
	s_ashr_i32 s66, s83, 31
	v_add_u32_e32 v0, s81, v73
	s_waitcnt lgkmcnt(0)
	s_barrier
	v_lshl_add_u64 v[100:101], s[0:1], 0, v[74:75]
	s_and_b64 s[0:1], s[40:41], exec
	s_movk_i32 s89, 0x200
	v_bfe_u32 v0, v0, 2, 4
	s_cselect_b32 s0, s89, 0xfffffe00
	v_or_b32_e32 v74, 64, v0
	v_sub_u32_e32 v189, 0, v0
	v_mov_b32_e32 v0, 0
	v_mul_hi_i32_i24_e32 v103, s0, v138
	v_mul_i32_i24_e32 v102, s0, v138
	v_mul_hi_i32_i24_e32 v105, s0, v139
	v_mul_i32_i24_e32 v104, s0, v139
	v_mul_hi_i32_i24_e32 v107, s0, v140
	v_mul_i32_i24_e32 v106, s0, v140
	v_mul_hi_i32_i24_e32 v109, s0, v141
	v_mul_i32_i24_e32 v108, s0, v141
	v_mul_hi_i32_i24_e32 v111, s0, v142
	v_mul_i32_i24_e32 v110, s0, v142
	v_mul_hi_i32_i24_e32 v113, s0, v143
	v_mul_i32_i24_e32 v112, s0, v143
	v_mul_hi_i32_i24_e32 v115, s0, v144
	v_mul_i32_i24_e32 v114, s0, v144
	v_mul_hi_i32_i24_e32 v117, s0, v145
	v_mul_i32_i24_e32 v116, s0, v145
	s_mov_b32 s67, 0
	s_movk_i32 s68, 0xfbf
	s_mov_b32 s69, 0
	s_mov_b32 s72, 0
	s_mov_b32 s70, 0
	v_mov_b32_e32 v1, v0
	v_mov_b32_e32 v2, v0
	v_mov_b32_e32 v3, v0
	v_mov_b32_e32 v4, v0
	v_mov_b32_e32 v5, v0
	v_mov_b32_e32 v6, v0
	v_mov_b32_e32 v7, v0
	v_mov_b32_e32 v8, v0
	v_mov_b32_e32 v9, v0
	v_mov_b32_e32 v10, v0
	v_mov_b32_e32 v11, v0
	v_mov_b32_e32 v12, v0
	v_mov_b32_e32 v13, v0
	v_mov_b32_e32 v14, v0
	v_mov_b32_e32 v15, v0
	v_mov_b32_e32 v16, v0
	v_mov_b32_e32 v17, v0
	v_mov_b32_e32 v18, v0
	v_mov_b32_e32 v19, v0
	v_mov_b32_e32 v20, v0
	v_mov_b32_e32 v21, v0
	v_mov_b32_e32 v22, v0
	v_mov_b32_e32 v23, v0
	v_mov_b32_e32 v24, v0
	v_mov_b32_e32 v25, v0
	v_mov_b32_e32 v26, v0
	v_mov_b32_e32 v27, v0
	v_mov_b32_e32 v28, v0
	v_mov_b32_e32 v29, v0
	v_mov_b32_e32 v30, v0
	v_mov_b32_e32 v31, v0
	v_and_b32_e32 v251, 3, v73
	v_and_b32_e32 v252, 48, v73
	v_add_u32_e32 v251, v251, v252
	v_add_u32_e32 v251, -4, v251
	v_and_b32_e32 v253, 16, v73
	v_cmp_ne_u32_e32 vcc, 0, v253
	v_and_b32_e32 v252, 3, v73
	v_add_u32_e32 v252, 28, v252
	v_cndmask_b32_e32 v251, v73, v251, vcc
	v_cndmask_b32_e64 v253, 0, 1.0, vcc
	v_cmp_lt_u32_e32 vcc, 31, v73
	v_lshlrev_b32_e32 v251, 2, v251
	v_lshlrev_b32_e32 v252, 2, v252
	v_cndmask_b32_e64 v245, 0, 1.0, vcc
	v_add_u32_e32 v248, v123, v182
	v_add_u32_e32 v249, v183, v127
	v_add_u32_e32 v250, v184, v127
	v_add_u32_e32 v33, 0xfbf, v189
	v_cndmask_b32_e64 v32, v33, v74, s[40:41]
	v_add_u32_e32 v32, s83, v32
	v_ashrrev_i32_e32 v33, 31, v32
	v_lshlrev_b64 v[34:35], 10, v[32:33]
	v_lshl_add_u64 v[234:235], v[88:89], 0, v[34:35]
	v_mad_i64_i32 v[236:237], s[0:1], v32, s79, v[90:91]
	v_mad_i64_i32 v[238:239], s[0:1], v32, s79, v[92:93]
	v_mad_i64_i32 v[240:241], s[0:1], v32, s79, v[94:95]
	v_lshl_add_u64 v[242:243], v[96:97], 0, v[34:35]
	v_lshl_add_u64 v[246:247], v[98:99], 0, v[34:35]
	s_and_b64 s[0:1], s[40:41], exec
	s_mov_b32 s98, 0x4000
	s_cselect_b32 s98, s98, 0xffffc000
	s_cselect_b32 s99, 0, -1
	s_mov_b32 s100, 0xc000
	s_cselect_b32 s100, s100, 0xffff4000
	s_cselect_b32 s101, 0, -1
	s_branch .LBB0_614

; template <bool RWKV> __device__ __forceinline__ void scan_item(LAS unsigned char* lds, const ScanSrc& S, int wid, int lane) {
;     ...
;     for (int c = 0; c < NCH; ++c) {
;         const int i1 = i0 == 2 ? 0 : i0 + 1, i2 = i1 == 2 ? 0 : i1 + 1;
;         if (is_ld) {
;             if (c + 3 < NCH) scan_load_finish<RWKV>(lds + ((b0 + 3) & 3) * SC_BUF, L, lt);
;             if (c + 4 < NCH) scan_load_issue<RWKV>(L, S, c + 4, lt); }
;         else if (is_prep) { if (c + 2 < NCH) scan_prep_m1<RWKV>(lds + ((b0 + 2) & 3) * SC_BUF, lds + SC_IMG + i2 * SW_SIZE, lane); }
;         else if (is_inv) { if (c + 1 < NCH) scan_prep_inv<RWKV>(lds + SC_IMG + i1 * SW_SIZE, lane); }
;         else if (wid < 2) scan_chunk<RWKV>(lds + b0 * SC_BUF, lds + SC_IMG + i0 * SW_SIZE, T, S, c, wid, lane);
.LBB0_614:
	s_add_i32 s0, s72, 1
	s_cmp_lg_u32 s72, 2
	s_cselect_b32 s71, s0, 0
	s_cmp_lt_i32 s3, 2
	s_cbranch_scc1 .Lrw_compute
	s_cmp_lt_i32 s3, 7
	s_cbranch_scc1 .LBB0_616
	s_cmp_lg_u32 s3, 7
	s_mov_b64 s[0:1], -1
	s_cselect_b64 s[42:43], -1, 0
	s_cbranch_execz .LBB0_617
	s_branch .LBB0_618

; __device__ __forceinline__ unsigned cvt2(float a, float b) { f32x2 v = {a, b}; bf16x2_t r = __builtin_convertvector(v, bf16x2_t); return __builtin_bit_cast(unsigned, r); }
; template <bool RWKV> __device__ __forceinline__ void scan_prep_inv(LAS unsigned char* img, int lane) {
;     const int r = lane & 31;
;     if (RWKV) {
;         const int sc = lane & 15; float X[16];
; #pragma unroll
;         for (int t = 15; t >= 0; --t) { float acc = (t == sc) ? 1.f : 0.f;
; #pragma unroll
;             for (int m4 = (t + 1) / 4; m4 < 4; ++m4) { const f32x4 gv = *(const LAS f32x4*)(img + SW_GR + (t * 16 + 4 * m4) * 4);
; #pragma unroll
;                 for (int q = 0; q < 4; ++q) if (4 * m4 + q > t) acc = fmaf(gv[q], X[4 * m4 + q], acc); }
;             X[t] = acc; }
;         if (lane < 32) { u32x4 p0, p1; const bool z = r >= 16;
;             p0.x = z ? 0u : cvt2(X[0], X[1]); p0.y = z ? 0u : cvt2(X[2], X[3]); p0.z = z ? 0u : cvt2(X[4], X[5]); p0.w = z ? 0u : cvt2(X[6], X[7]);
;             p1.x = z ? 0u : cvt2(X[8], X[9]); p1.y = z ? 0u : cvt2(X[10], X[11]); p1.z = z ? 0u : cvt2(X[12], X[13]); p1.w = z ? 0u : cvt2(X[14], X[15]);
;             *(LAS u32x4*)(img + SW_TIT + r * 48) = p0; *(LAS u32x4*)(img + SW_TIT + r * 48 + 16) = p1; }
;     }
; }
.LBB0_620:
	s_mov_b64 s[0:1], -1
	s_and_b64 vcc, exec, s[74:75]
	s_cbranch_vccz .LBB0_632
	s_and_b64 vcc, exec, s[90:91]
	s_cbranch_vccz .LBB0_625
.LBB0_624:
	s_mov_b64 s[0:1], 0
.LBB0_625:
	s_andn2_b64 vcc, exec, s[0:1]
	s_cbranch_vccnz .LBB0_631
	s_cmpk_eq_i32 s68, 0xffcf
	s_cbranch_scc1 .LBB0_630
	s_mul_i32 s42, s71, 0x1600
	s_add_i32 s42, s42, 0x11400
	v_and_b32_e32 v234, 3, v73
	v_lshrrev_b32_e32 v235, 2, v73
	v_lshl_add_u32 v228, v234, 6, s42
	ds_read_b128 v[68:71], v228 offset:816
	ds_read_b128 v[64:67], v228 offset:560
	ds_read_b128 v[56:59], v228 offset:304
	ds_read_b128 v[44:47], v228 offset:48
	ds_read_b128 v[60:63], v228 offset:544
	ds_read_b128 v[52:55], v228 offset:288
	ds_read_b128 v[40:43], v228 offset:32
	ds_read_b128 v[48:51], v228 offset:272
	ds_read_b128 v[36:39], v228 offset:16
	ds_read_b128 v[32:35], v228
	v_sub_u32_e32 v236, v235, v234
	v_cmp_eq_u32_e64 s[0:1], 0, v236
	v_cmp_eq_u32_e64 s[100:101], 4, v236
	v_cmp_eq_u32_e32 vcc, 8, v236
	v_mul_u32_u24_e32 v229, 48, v235
	v_cndmask_b32_e64 v222, 0, 1.0, s[0:1]
	v_cndmask_b32_e64 v223, 0, 1.0, s[100:101]
	v_cndmask_b32_e64 v224, 0, 1.0, vcc
	v_cmp_eq_u32_e32 vcc, 12, v236
	v_lshl_add_u32 v237, v234, 1, s42
	v_lshl_add_u32 v238, v234, 3, s42
	v_add_u32_e32 v230, v229, v238
	v_add_u32_e32 v229, v229, v237
	v_cndmask_b32_e64 v225, 0, 1.0, vcc
	v_mov_b32_e32 v232, 0
	v_mov_b32_e32 v233, 0
	s_waitcnt lgkmcnt(6)
	v_mov_b32_dpp v226, v225 quad_perm:[3,3,3,3] row_mask:0xf bank_mask:0xf
	v_fmac_f32_e32 v225, v71, v226
	v_fmac_f32_e32 v224, v67, v226
	v_fmac_f32_e32 v223, v59, v226
	v_fmac_f32_e32 v222, v47, v226
	v_mov_b32_dpp v226, v225 quad_perm:[2,2,2,2] row_mask:0xf bank_mask:0xf
	v_fmac_f32_e32 v225, v70, v226
	v_fmac_f32_e32 v224, v66, v226
	v_fmac_f32_e32 v223, v58, v226
	v_fmac_f32_e32 v222, v46, v226
	v_mov_b32_dpp v226, v225 quad_perm:[1,1,1,1] row_mask:0xf bank_mask:0xf
	v_fmac_f32_e32 v225, v69, v226
	v_fmac_f32_e32 v224, v65, v226
	v_fmac_f32_e32 v223, v57, v226
	v_fmac_f32_e32 v222, v45, v226
	v_mov_b32_dpp v226, v225 quad_perm:[0,0,0,0] row_mask:0xf bank_mask:0xf
	v_fmac_f32_e32 v224, v64, v226
	v_fmac_f32_e32 v223, v56, v226
	v_fmac_f32_e32 v222, v44, v226
	s_waitcnt lgkmcnt(3)
	v_mov_b32_dpp v226, v224 quad_perm:[3,3,3,3] row_mask:0xf bank_mask:0xf
	v_fmac_f32_e32 v224, v63, v226
	v_fmac_f32_e32 v223, v55, v226
	v_fmac_f32_e32 v222, v43, v226
	v_mov_b32_dpp v226, v224 quad_perm:[2,2,2,2] row_mask:0xf bank_mask:0xf
	v_fmac_f32_e32 v224, v62, v226
	v_fmac_f32_e32 v223, v54, v226
	v_fmac_f32_e32 v222, v42, v226
	v_mov_b32_dpp v226, v224 quad_perm:[1,1,1,1] row_mask:0xf bank_mask:0xf
	v_fmac_f32_e32 v224, v61, v226
	v_fmac_f32_e32 v223, v53, v226
	v_fmac_f32_e32 v222, v41, v226
	v_mov_b32_dpp v226, v224 quad_perm:[0,0,0,0] row_mask:0xf bank_mask:0xf
	v_fmac_f32_e32 v223, v52, v226
	v_fmac_f32_e32 v222, v40, v226
	s_nop 0
	s_waitcnt lgkmcnt(1)
	v_mov_b32_dpp v226, v223 quad_perm:[3,3,3,3] row_mask:0xf bank_mask:0xf
	v_fmac_f32_e32 v223, v51, v226
	v_fmac_f32_e32 v222, v39, v226
	s_nop 0
	v_mov_b32_dpp v226, v223 quad_perm:[2,2,2,2] row_mask:0xf bank_mask:0xf
	v_fmac_f32_e32 v223, v50, v226
	v_fmac_f32_e32 v222, v38, v226
	s_nop 0
	v_mov_b32_dpp v226, v223 quad_perm:[1,1,1,1] row_mask:0xf bank_mask:0xf
	v_fmac_f32_e32 v223, v49, v226
	v_fmac_f32_e32 v222, v37, v226
	s_nop 0
	v_mov_b32_dpp v226, v223 quad_perm:[0,0,0,0] row_mask:0xf bank_mask:0xf
	v_fmac_f32_e32 v222, v36, v226
	s_nop 1
	s_waitcnt lgkmcnt(0)
	v_mov_b32_dpp v226, v222 quad_perm:[3,3,3,3] row_mask:0xf bank_mask:0xf
	v_fmac_f32_e32 v222, v35, v226
	s_nop 1
	v_mov_b32_dpp v226, v222 quad_perm:[2,2,2,2] row_mask:0xf bank_mask:0xf
	v_fmac_f32_e32 v222, v34, v226
	s_nop 1
	v_mov_b32_dpp v226, v222 quad_perm:[1,1,1,1] row_mask:0xf bank_mask:0xf
	v_fmac_f32_e32 v222, v33, v226
	v_cvt_pk_bf16_f32 v236, v222, v222
	v_cvt_pk_bf16_f32 v237, v223, v223
	v_cvt_pk_bf16_f32 v238, v224, v224
	v_cvt_pk_bf16_f32 v239, v225, v225
	ds_write_b16 v229, v236 offset:4096
	ds_write_b16 v229, v237 offset:4104
	ds_write_b16 v229, v238 offset:4112
	ds_write_b16 v229, v239 offset:4120
	ds_write_b64 v230, v[232:233] offset:4864
.LBB0_630:
	s_branch .LBB0_613

; template <bool RWKV> __device__ __forceinline__ void scan_load_issue(ScanLd& L, const ScanSrc& S, int chunk, int lt) {
;     const int lw = lt >> 6, lane = lt & 63, sl = lane >> 2, col = 16 * lw + 4 * (lane & 3), s = chunk * SC_CH + sl; const size_t tok = (size_t)(S.tokbase + (S.rev ? T_SEQ - 1 - s : s));
;     L.rd = *(const u32x2*)(S.v[0] + tok * S.ld[0] + col); L.rk = *(const u32x2*)(S.v[1] + tok * S.ld[1] + col); L.rr = *(const u32x2*)(S.v[4] + tok * S.ld[4] + col); L.rv = *(const u32x2*)(S.v[5] + tok * S.ld[5] + col);
;     L.rkk = L.rk; L.rnb = L.rk;
;     if (RWKV) { L.rkk = *(const u32x2*)(S.v[2] + tok * S.ld[2] + col); L.rnb = *(const u32x2*)(S.v[3] + tok * S.ld[3] + col); }
; }
; template <bool RWKV> __device__ __forceinline__ void scan_load_finish(LAS unsigned char* buf, const ScanLd& L, int lt) {
;     const int lw = lt >> 6, lane = lt & 63, sl = lane >> 2, col = 16 * lw + 4 * (lane & 3);
;     float d[4], c[4], k[4], r[4], v[4], kk[4], nb[4];
;     unpack4(L.rd, d); unpack4(L.rk, k); unpack4(L.rr, r); unpack4(L.rv, v); unpack4(L.rkk, kk); unpack4(L.rnb, nb);
; #pragma unroll
;     for (int i = 0; i < 4; ++i) c[i] = d[i];
; #pragma unroll
;     for (int dl = 4; dl < 64; dl <<= 1)
; #pragma unroll
;         for (int i = 0; i < 4; ++i) { const float t = __shfl_up(c[i], dl); c[i] += (lane >= dl) ? t : 0.f; }
;     float o1[4], o2[4], o3[4], o4[4]; f32x4 we;
; #pragma unroll
;     for (int i = 0; i < 4; ++i) { const float W = __expf(-c[i]), iW = __expf(c[i]), Wp = __expf(d[i] - c[i]); o1[i] = RWKV ? kk[i] * Wp : 0.f; o2[i] = RWKV ? nb[i] * iW : 0.f; o3[i] = k[i] * iW; o4[i] = r[i] * W; we[i] = W; }
;     u32x2 w;
;     w.x = cvt2(o1[0], o1[1]); w.y = cvt2(o1[2], o1[3]); *(LAS u32x2*)(buf + SB_XA + sl * 144 + col * 2) = w;
;     w.x = cvt2(o4[0], o4[1]); w.y = cvt2(o4[2], o4[3]); *(LAS u32x2*)(buf + SB_XA + (16 + sl) * 144 + col * 2) = w;
;     w.x = cvt2(o2[0], o2[1]); w.y = cvt2(o2[2], o2[3]); *(LAS u32x2*)(buf + SB_XB + sl * 144 + col * 2) = w;
;     w.x = cvt2(o3[0], o3[1]); w.y = cvt2(o3[2], o3[3]); *(LAS u32x2*)(buf + SB_XB + (16 + sl) * 144 + col * 2) = w;
; #pragma unroll
;     for (int i = 0; i < 4; ++i) {
;         *(LAS unsigned short*)(buf + SB_XBT + (col + i) * 80 + sl * 2) = (unsigned short)(cvt2(o2[i], 0.f) & 0xffffu);
.LBB0_640:
	s_cmpk_gt_u32 s69, 0xfc
	s_cbranch_scc1 .LBB0_613
	s_add_i32 s0, s70, -1
	s_and_b32 s0, s0, 3
	s_mulk_i32 s0, 0x4500
	v_add_u32_e32 v190, s0, v250
	s_waitcnt vmcnt(0)
	ds_write_b16 v190, v82 offset:14336
	ds_write_b16_d16_hi v190, v82 offset:14384
	ds_write_b16 v190, v83 offset:14432
	ds_write_b16_d16_hi v190, v83 offset:14480
	v_lshlrev_b32_e32 v32, 16, v76
	v_and_b32_e32 v33, 0xffff0000, v76
	v_lshlrev_b32_e32 v34, 16, v77
	v_and_b32_e32 v35, 0xffff0000, v77
	v_lshlrev_b32_e32 v36, 16, v78
	v_and_b32_e32 v37, 0xffff0000, v78
	v_lshlrev_b32_e32 v38, 16, v79
	v_and_b32_e32 v39, 0xffff0000, v79
	v_lshlrev_b32_e32 v40, 16, v80
	v_and_b32_e32 v41, 0xffff0000, v80
	v_lshlrev_b32_e32 v42, 16, v81
	v_and_b32_e32 v43, 0xffff0000, v81
	v_lshlrev_b32_e32 v44, 16, v84
	v_and_b32_e32 v45, 0xffff0000, v84
	v_lshlrev_b32_e32 v46, 16, v85
	v_and_b32_e32 v47, 0xffff0000, v85
	v_lshlrev_b32_e32 v48, 16, v86
	v_and_b32_e32 v49, 0xffff0000, v86
	v_lshlrev_b32_e32 v50, 16, v87
	v_and_b32_e32 v51, 0xffff0000, v87
	s_cmpk_gt_u32 s69, 0xfb
	s_cbranch_scc1 .Lrw_ldfin
	global_load_dwordx2 v[76:77], v[234:235], off
	global_load_dwordx2 v[78:79], v[236:237], off
	global_load_dwordx2 v[80:81], v[238:239], off
	global_load_dwordx2 v[82:83], v[240:241], off
	global_load_dwordx2 v[84:85], v[242:243], off
	global_load_dwordx2 v[86:87], v[246:247], off
	v_lshl_add_u64 v[234:235], v[234:235], 0, s[98:99]
	v_lshl_add_u64 v[236:237], v[236:237], 0, s[100:101]
	v_lshl_add_u64 v[238:239], v[238:239], 0, s[100:101]
	v_lshl_add_u64 v[240:241], v[240:241], 0, s[100:101]
	v_lshl_add_u64 v[242:243], v[242:243], 0, s[98:99]
	v_lshl_add_u64 v[246:247], v[246:247], 0, s[98:99]
.Lrw_ldfin:
	v_mul_f32_e32 v52, 0x3fb8aa3b, v32
	v_mul_f32_e32 v53, 0x3fb8aa3b, v33
	v_mul_f32_e32 v54, 0x3fb8aa3b, v34
	v_mul_f32_e32 v55, 0x3fb8aa3b, v35
	v_add_f32_dpp v52, v52, v52 row_shr:4 row_mask:0xf bank_mask:0xf
	v_add_f32_dpp v53, v53, v53 row_shr:4 row_mask:0xf bank_mask:0xf
	v_add_f32_dpp v54, v54, v54 row_shr:4 row_mask:0xf bank_mask:0xf
	v_add_f32_dpp v55, v55, v55 row_shr:4 row_mask:0xf bank_mask:0xf
	v_add_f32_dpp v52, v52, v52 row_shr:8 row_mask:0xf bank_mask:0xf
	v_add_f32_dpp v53, v53, v53 row_shr:8 row_mask:0xf bank_mask:0xf
	v_add_f32_dpp v54, v54, v54 row_shr:8 row_mask:0xf bank_mask:0xf
	v_add_f32_dpp v55, v55, v55 row_shr:8 row_mask:0xf bank_mask:0xf
	ds_bpermute_b32 v60, v251, v52
	ds_bpermute_b32 v61, v251, v53
	ds_bpermute_b32 v62, v251, v54
	ds_bpermute_b32 v63, v251, v55
	s_waitcnt lgkmcnt(0)
	v_fmac_f32_e32 v52, v60, v253
	v_fmac_f32_e32 v53, v61, v253
	v_fmac_f32_e32 v54, v62, v253
	v_fmac_f32_e32 v55, v63, v253
	ds_bpermute_b32 v60, v252, v52
	ds_bpermute_b32 v61, v252, v53
	ds_bpermute_b32 v62, v252, v54
	ds_bpermute_b32 v63, v252, v55
	s_waitcnt lgkmcnt(0)
	v_fmac_f32_e32 v52, v60, v245
	v_fmac_f32_e32 v53, v61, v245
	v_fmac_f32_e32 v54, v62, v245
	v_fmac_f32_e32 v55, v63, v245
	v_fmamk_f32 v56, v32, 0xbfb8aa3b, v52
	v_fmamk_f32 v57, v33, 0xbfb8aa3b, v53
	v_fmamk_f32 v58, v34, 0xbfb8aa3b, v54
	v_fmamk_f32 v59, v35, 0xbfb8aa3b, v55
	v_exp_f32_e64 v64, -v52
	v_exp_f32_e64 v65, -v53
	v_exp_f32_e64 v66, -v54
	v_exp_f32_e64 v67, -v55
	v_exp_f32_e32 v68, v52
	v_exp_f32_e32 v69, v53
	v_exp_f32_e32 v70, v54
	v_exp_f32_e32 v71, v55
	v_exp_f32_e64 v192, -v56
	v_exp_f32_e64 v193, -v57
	v_exp_f32_e64 v194, -v58
	v_exp_f32_e64 v195, -v59
	v_add_u32_e32 v191, s0, v248
	v_pk_mul_f32 v[208:209], v[64:65], v[40:41]
	v_pk_mul_f32 v[210:211], v[66:67], v[42:43]
	v_pk_mul_f32 v[200:201], v[68:69], v[48:49]
	v_pk_mul_f32 v[202:203], v[70:71], v[50:51]
	v_pk_mul_f32 v[204:205], v[68:69], v[36:37]
	v_pk_mul_f32 v[206:207], v[70:71], v[38:39]
	v_pk_mul_f32 v[196:197], v[192:193], v[44:45]
	v_pk_mul_f32 v[198:199], v[194:195], v[46:47]
	v_cvt_pk_bf16_f32 v218, v208, v209
	v_cvt_pk_bf16_f32 v219, v210, v211
	v_cvt_pk_bf16_f32 v214, v200, v201
	v_cvt_pk_bf16_f32 v215, v202, v203
	v_cvt_pk_bf16_f32 v216, v204, v205
	v_cvt_pk_bf16_f32 v217, v206, v207
	v_cvt_pk_bf16_f32 v212, v196, v197
	v_cvt_pk_bf16_f32 v213, v198, v199
	v_add_u32_e32 v220, 0x900, v191
	v_add_u32_e32 v221, s0, v249
	ds_write2st64_b64 v220, v[218:219], v[216:217] offset1:9
	ds_write2st64_b64 v191, v[212:213], v[214:215] offset1:9
	ds_write_b16 v221, v214 offset:9216
	ds_write_b16_d16_hi v221, v214 offset:9296
	ds_write_b16 v221, v215 offset:9376
	ds_write_b16_d16_hi v221, v215 offset:9456
	ds_write_b16 v221, v216 offset:9248
	ds_write_b16_d16_hi v221, v216 offset:9328
	ds_write_b16 v221, v217 offset:9408
	ds_write_b16_d16_hi v221, v217 offset:9488
	s_and_saveexec_b64 s[42:43], s[14:15]
	v_add_u32_e32 v222, s0, v188
	ds_write_b128 v222, v[64:67] offset:17408
	s_or_b64 exec, exec, s[42:43]
	s_branch .LBB0_613
; template <bool RWKV> __device__ __forceinline__ void scan_chunk(const LAS unsigned char* buf, const LAS unsigned char* img, f32x16 (&T)[2], const ScanSrc& S, int chunk, int w, int lane) {
;     const int r = lane & 31, h = lane >> 5;
;     f32x16 zero;
; #pragma unroll
;     for (int i = 0; i < 16; ++i) zero[i] = 0.f;
;     const bf16x8 vb = *(const LAS bf16x8*)(buf + SB_VT + (32 * w + r) * 48 + 16 * h);
;     f32x16 ry = zero, ry2 = zero;
; #pragma unroll
;     for (int kb = 0; kb < 2; ++kb) {
;         const bf16x8 b0 = pack8r(T[0][8 * kb], T[0][8 * kb + 1], T[0][8 * kb + 2], T[0][8 * kb + 3], T[0][8 * kb + 4], T[0][8 * kb + 5], T[0][8 * kb + 6], T[0][8 * kb + 7]);
;         const bf16x8 b1 = pack8r(T[1][8 * kb], T[1][8 * kb + 1], T[1][8 * kb + 2], T[1][8 * kb + 3], T[1][8 * kb + 4], T[1][8 * kb + 5], T[1][8 * kb + 6], T[1][8 * kb + 7]);
;         ry = MFMA32(lds_aperm(buf + SB_XA + r * 144 + (16 * kb) * 2, h), b0, ry);
;         ry2 = MFMA32(lds_aperm(buf + SB_XA + r * 144 + (32 + 16 * kb) * 2, h), b1, ry2); }
;     { const bf16x8 a = *(const LAS bf16x8*)(img + SW_HT + r * 48 + 16 * h); ry = MFMA32(a, vb, ry); }
; #pragma unroll
;     for (int i = 0; i < 16; ++i) ry[i] += ry2[i];
;     bf16x8 ub;
;     if (RWKV) {
;         const bf16x8 rb = pack8r(ry[0], ry[1], ry[2], ry[3], ry[4], ry[5], ry[6], ry[7]);
;         const f32x16 ua = MFMA32(lds_aperm(img + SW_TIT + r * 48, h), rb, zero);
;         ub = pack8r(ua[0], ua[1], ua[2], ua[3], ua[4], ua[5], ua[6], ua[7]);
;         ry = MFMA32(lds_aperm(img + SW_GYT + r * 48, h), ub, ry);
;     }
;     {
;         const int s0 = chunk * SC_CH; const long tok0 = (long)S.tokbase + (S.rev ? T_SEQ - 1 - s0 : s0), dstep = S.rev ? -512 : 512;
;         bf16_t* op = S.out + tok0 * 512 + 32 * w + r;
; #pragma unroll
;         for (int q = 8; q < 16; ++q) { const int s = (q & 3) + 8 * ((q >> 2) - 2) + 4 * h; op[s * dstep] = (bf16_t)(cvt2(ry[q], 0.f) & 0xffffu); }
;     }
; #pragma unroll
;     for (int jt = 0; jt < 2; ++jt) {
;         if (RWKV) T[jt] = MFMA32(lds_aperm(buf + SB_XBT + (32 * jt + r) * 80, h), ub, T[jt]);
;         { const bf16x8 a = *(const LAS bf16x8*)(buf + SB_XBT + (32 * jt + r) * 80 + 32 + 16 * h); T[jt] = MFMA32(a, vb, T[jt]); }
; #pragma unroll
;         for (int g = 0; g < 4; ++g) { const f32x4 we = *(const LAS f32x4*)(buf + SB_WE + (32 * jt + 8 * g + 4 * h) * 4);
; #pragma unroll
.Lrw_compute:
	s_mul_i32 s0, s70, 0x4500
	s_mul_i32 s1, s72, 0x1600
	v_add3_u32 v242, s0, v135, v136
	v_add_u32_e32 v243, s0, v134
	ds_read2_b64 v[32:35], v242 offset1:2
	ds_read2_b64 v[36:39], v242 offset0:4 offset1:6
	v_add_u32_e32 v245, v243, v152
	ds_read2_b64 v[40:43], v242 offset0:8 offset1:10
	ds_read2_b64 v[44:47], v242 offset0:12 offset1:14
	ds_read_b128 v[48:51], v245 offset:14336
	v_add3_u32 v245, s1, v177, v134
	v_cvt_pk_bf16_f32 v64, v0, v1
	v_cvt_pk_bf16_f32 v65, v2, v3
	v_cvt_pk_bf16_f32 v66, v4, v5
	v_cvt_pk_bf16_f32 v67, v6, v7
	ds_read_b128 v[52:55], v245 offset:1024
	v_add3_u32 v245, s1, v177, v136
	v_add_u32_e32 v242, 0x1000, v245
	ds_read2_b64 v[56:59], v242 offset1:2
	v_add_u32_e32 v242, 0x800, v245
	ds_read2_b64 v[60:63], v242 offset0:64 offset1:66
	v_cvt_pk_bf16_f32 v68, v8, v9
	v_cvt_pk_bf16_f32 v69, v10, v11
	v_cvt_pk_bf16_f32 v70, v12, v13
	v_cvt_pk_bf16_f32 v71, v14, v15
	v_add3_u32 v242, s0, v153, v134
	ds_read_b128 v[250:253], v242 offset:9248
	v_add3_u32 v242, s0, v154, v134
	ds_read_b128 v[118:121], v242 offset:9248
	v_cvt_pk_bf16_f32 v190, v16, v17
	v_cvt_pk_bf16_f32 v191, v18, v19
	v_cvt_pk_bf16_f32 v192, v20, v21
	v_cvt_pk_bf16_f32 v193, v22, v23
	s_waitcnt lgkmcnt(9)
	v_mfma_f32_32x32x16_bf16 v[198:213], v[32:35], v[64:67], 0
	v_cvt_pk_bf16_f32 v194, v24, v25
	v_cvt_pk_bf16_f32 v195, v26, v27
	v_cvt_pk_bf16_f32 v196, v28, v29
	v_cvt_pk_bf16_f32 v197, v30, v31
	v_add3_u32 v242, s0, v153, v136
	v_add_u32_e32 v242, 0x2000, v242
	ds_read2_b64 v[238:241], v242 offset0:128 offset1:130
	v_add3_u32 v242, s0, v154, v136
	v_add_u32_e32 v242, 0x2000, v242
	ds_read2_b64 v[246:249], v242 offset0:128 offset1:130
	s_waitcnt lgkmcnt(10)
	v_mfma_f32_32x32x16_bf16 v[198:213], v[36:39], v[68:71], v[198:213]
	s_waitcnt lgkmcnt(9)
	v_mfma_f32_32x32x16_bf16 v[198:213], v[40:43], v[190:193], v[198:213]
	s_waitcnt lgkmcnt(8)
	v_mfma_f32_32x32x16_bf16 v[198:213], v[44:47], v[194:197], v[198:213]
	s_waitcnt lgkmcnt(6)
	v_mfma_f32_32x32x16_bf16 v[198:213], v[52:55], v[48:51], v[198:213]
	s_waitcnt lgkmcnt(3)
	v_mfma_f32_32x32x16_bf16 v[0:15], v[250:253], v[48:51], v[0:15]
	ds_read_b128 v[32:35], v243 offset:17408
	ds_read_b128 v[36:39], v243 offset:17440
	ds_read_b128 v[40:43], v243 offset:17472
	ds_read_b128 v[44:47], v243 offset:17504
	ds_read_b128 v[64:67], v243 offset:17536
	ds_read_b128 v[68:71], v243 offset:17568
	ds_read_b128 v[190:193], v243 offset:17600
	ds_read_b128 v[194:197], v243 offset:17632
	s_nop 2
	v_cvt_pk_bf16_f32 v214, v198, v199
	v_cvt_pk_bf16_f32 v215, v200, v201
	v_cvt_pk_bf16_f32 v216, v202, v203
	v_cvt_pk_bf16_f32 v217, v204, v205
	s_nop 1
	v_mfma_f32_32x32x16_bf16 v[222:237], v[56:59], v[214:217], 0
	s_waitcnt lgkmcnt(10)
	v_mfma_f32_32x32x16_bf16 v[16:31], v[118:121], v[48:51], v[16:31]
	s_add_i32 s1, s68, 64
	s_and_b64 s[42:43], s[40:41], exec
	s_cselect_b32 s1, s67, s1
	s_add_u32 s42, s1, s83
	s_addc_u32 s43, 0, s66
	s_lshl_b64 s[42:43], s[42:43], 10
	v_lshl_add_u64 v[242:243], v[100:101], 0, s[42:43]
	v_lshl_add_u64 v[52:53], v[102:103], 1, v[242:243]
	v_lshl_add_u64 v[54:55], v[104:105], 1, v[242:243]
	v_lshl_add_u64 v[250:251], v[106:107], 1, v[242:243]
	v_lshl_add_u64 v[252:253], v[108:109], 1, v[242:243]
	v_lshl_add_u64 v[56:57], v[110:111], 1, v[242:243]
	v_lshl_add_u64 v[58:59], v[112:113], 1, v[242:243]
	v_lshl_add_u64 v[214:215], v[114:115], 1, v[242:243]
	v_lshl_add_u64 v[216:217], v[116:117], 1, v[242:243]
	v_cvt_pk_bf16_f32 v218, v222, v223
	v_cvt_pk_bf16_f32 v219, v224, v225
	v_cvt_pk_bf16_f32 v220, v226, v227
	v_cvt_pk_bf16_f32 v221, v228, v229
	s_nop 1
	v_mfma_f32_32x32x16_bf16 v[198:213], v[60:63], v[218:221], v[198:213]
	s_waitcnt lgkmcnt(9)
	v_mfma_f32_32x32x16_bf16 v[0:15], v[238:241], v[218:221], v[0:15]
	s_waitcnt lgkmcnt(8)
	v_mfma_f32_32x32x16_bf16 v[16:31], v[246:249], v[218:221], v[16:31]
	s_nop 7
	v_cvt_pk_bf16_f32 v218, v206, v206
	global_store_short v[52:53], v218, off
	v_cvt_pk_bf16_f32 v219, v207, v207
	global_store_short v[54:55], v219, off
	v_cvt_pk_bf16_f32 v220, v208, v208
	global_store_short v[250:251], v220, off
	v_cvt_pk_bf16_f32 v221, v209, v209
	global_store_short v[252:253], v221, off
	v_cvt_pk_bf16_f32 v238, v210, v210
	global_store_short v[56:57], v238, off
	v_cvt_pk_bf16_f32 v239, v211, v211
	global_store_short v[58:59], v239, off
	v_cvt_pk_bf16_f32 v240, v212, v212
	global_store_short v[214:215], v240, off
	v_cvt_pk_bf16_f32 v241, v213, v213
	global_store_short v[216:217], v241, off
	s_waitcnt lgkmcnt(0)
	v_pk_mul_f32 v[0:1], v[0:1], v[32:33]
	v_pk_mul_f32 v[2:3], v[2:3], v[34:35]
	v_pk_mul_f32 v[4:5], v[4:5], v[36:37]
	v_pk_mul_f32 v[6:7], v[6:7], v[38:39]
	v_pk_mul_f32 v[8:9], v[8:9], v[40:41]
	v_pk_mul_f32 v[10:11], v[10:11], v[42:43]
	v_pk_mul_f32 v[12:13], v[12:13], v[44:45]
	v_pk_mul_f32 v[14:15], v[14:15], v[46:47]
	v_pk_mul_f32 v[16:17], v[16:17], v[64:65]
	v_pk_mul_f32 v[18:19], v[18:19], v[66:67]
	v_pk_mul_f32 v[20:21], v[20:21], v[68:69]
	v_pk_mul_f32 v[22:23], v[22:23], v[70:71]
	v_pk_mul_f32 v[24:25], v[24:25], v[190:191]
	v_pk_mul_f32 v[26:27], v[26:27], v[192:193]
	v_pk_mul_f32 v[28:29], v[28:29], v[194:195]
	v_pk_mul_f32 v[30:31], v[30:31], v[196:197]
	s_branch .LBB0_613

; __global__ void __launch_bounds__(512, 2) hymba_fwd(Params p) {
;     extern __shared__ __attribute__((aligned(16))) unsigned char lds_raw[];
	.amdhsa_kernel _Z9hymba_fwd6Params
		.amdhsa_group_segment_fixed_size 0
		.amdhsa_private_segment_fixed_size 0
		.amdhsa_kernarg_size 512
		.amdhsa_user_sgpr_count 2
		.amdhsa_user_sgpr_dispatch_ptr 0
		.amdhsa_user_sgpr_queue_ptr 0
		.amdhsa_user_sgpr_kernarg_segment_ptr 1
		.amdhsa_user_sgpr_dispatch_id 0
		.amdhsa_user_sgpr_kernarg_preload_length 0
		.amdhsa_user_sgpr_kernarg_preload_offset 0
		.amdhsa_user_sgpr_private_segment_size 0
		.amdhsa_uses_dynamic_stack 0
		.amdhsa_enable_private_segment 0
		.amdhsa_system_sgpr_workgroup_id_x 1
		.amdhsa_system_sgpr_workgroup_id_y 0
		.amdhsa_system_sgpr_workgroup_id_z 0
		.amdhsa_system_sgpr_workgroup_info 0
		.amdhsa_system_vgpr_workitem_id 2
		.amdhsa_next_free_vgpr 256
		.amdhsa_next_free_sgpr 102
		.amdhsa_accum_offset 256
		.amdhsa_reserve_vcc 1
		.amdhsa_float_round_mode_32 0
		.amdhsa_float_round_mode_16_64 0
		.amdhsa_float_denorm_mode_32 3
		.amdhsa_float_denorm_mode_16_64 3
		.amdhsa_dx10_clamp 1
		.amdhsa_ieee_mode 1
		.amdhsa_fp16_overflow 0
		.amdhsa_tg_split 0
		.amdhsa_exception_fp_ieee_invalid_op 0
		.amdhsa_exception_fp_denorm_src 0
		.amdhsa_exception_fp_ieee_div_zero 0
		.amdhsa_exception_fp_ieee_overflow 0
		.amdhsa_exception_fp_ieee_underflow 0
		.amdhsa_exception_fp_ieee_inexact 0
		.amdhsa_exception_int_div_zero 0
	.end_amdhsa_kernel

; __global__ void __launch_bounds__(512, 2) hymba_fwd(Params p) {
;     extern __shared__ __attribute__((aligned(16))) unsigned char lds_raw[];
amdhsa.kernels:
  - .agpr_count:     0
    .args:
      - .offset:         0
        .size:           256
        .value_kind:     by_value
      - .offset:         256
        .size:           4
        .value_kind:     hidden_block_count_x
      - .offset:         260
        .size:           4
        .value_kind:     hidden_block_count_y
      - .offset:         264
        .size:           4
        .value_kind:     hidden_block_count_z
      - .offset:         268
        .size:           2
        .value_kind:     hidden_group_size_x
      - .offset:         270
        .size:           2
        .value_kind:     hidden_group_size_y
      - .offset:         272
        .size:           2
        .value_kind:     hidden_group_size_z
      - .offset:         274
        .size:           2
        .value_kind:     hidden_remainder_x
      - .offset:         276
        .size:           2
        .value_kind:     hidden_remainder_y
      - .offset:         278
        .size:           2
        .value_kind:     hidden_remainder_z
      - .offset:         296
        .size:           8
        .value_kind:     hidden_global_offset_x
      - .offset:         304
        .size:           8
        .value_kind:     hidden_global_offset_y
      - .offset:         312
        .size:           8
        .value_kind:     hidden_global_offset_z
      - .offset:         320
        .size:           2
        .value_kind:     hidden_grid_dims
      - .offset:         344
        .size:           8
        .value_kind:     hidden_multigrid_sync_arg
      - .offset:         376
        .size:           4
        .value_kind:     hidden_dynamic_lds_size
    .group_segment_fixed_size: 0
    .kernarg_segment_align: 8
    .kernarg_segment_size: 512
    .language:       OpenCL C
    .language_version:
      - 2
      - 0
    .max_flat_workgroup_size: 512
    .name:           _Z9hymba_fwd6Params
    .private_segment_fixed_size: 0
    .sgpr_count:     108
    .sgpr_spill_count: 85
    .symbol:         _Z9hymba_fwd6Params.kd
    .uniform_work_group_size: 1
    .uses_dynamic_stack: false
    .vgpr_count:     256
    .vgpr_spill_count: 0
    .wavefront_size: 64
